# attention steady loop: DMA source addresses from SGPR bases (saddr form, no 64-bit VALU adds); cross-half row-max combine moved into the rare rescale path
# speedup vs baseline: 1.0156x; 1.0010x over previous
; #define WAIT_BAR(N) asm volatile("s_waitcnt vmcnt(" #N ") lgkmcnt(0)\n\ts_barrier":::"memory")
;   #define DMA_K(t,slot) glds16(ksrc+(long)(t)*4096,(unsigned)__builtin_amdgcn_readfirstlane(kdst+(slot)))
;   #define DMA_V(t,slot) do{ glds16(vsrc+(long)(t)*8192,(unsigned)__builtin_amdgcn_readfirstlane(vdst+2*(slot))); glds16(vsrc+(long)(t)*8192+4096,(unsigned)__builtin_amdgcn_readfirstlane(vdst+2*(slot)+8192)); }while(0)
;   #define CMASK(P0,P1,t) do{int jb_=(t)-(NT-4); if(jb_>=-2&&(32*wid-64*jb_<176||64*jb_+63>32*wid))cmask(P0,P1,jb_,qrel,hi,btab);}while(0)
;   #define RESC() do{ if(resc){ asm volatile("s_waitcnt lgkmcnt(0)":::"memory"); \
;       _Pragma("unroll") for(int d_=0;d_<4;++d_) _Pragma("unroll") for(int r=0;r<16;++r)o[d_][r]*=wsf[crow(r,hi)]; } }while(0)
;   #define ROT() do{sl_prev=sl_cur;sl_cur=sl_next;sl_next=(sl_next==(NSLOT-1)*SLOTB)?0:sl_next+SLOTB;}while(0)
;   #define CMASK(P0,P1,t) do{}while(0)
;   #define CMASK(P0,P1,t) do{int jb_=(t)-(NT-4); if(jb_>=-2&&(32*wid-64*jb_<176||64*jb_+63>32*wid))cmask(P0,P1,jb_,qrel,hi,btab);}while(0)
; template<int THRL> __device__ __forceinline__ void attn_unit(int b,int hc,int qb,const bf16*Q,const bf16*__restrict__ K,const bf16*__restrict__ V,bf16*O,char*shm){
;     ...
;   qkt(pA0,pA1,Kbase,qr,zero16,r32,hi);asm volatile("s_nop 15\n\ts_nop 7":"+v"(pA0),"+v"(pA1));CMASK(pA0,pA1,0);
;   { const float rm=rowmax(pA0,pA1); mhat=rm;
;     _Pragma("unroll") for(int r=0;r<16;++r){pA0[r]=__builtin_amdgcn_exp2f(pA0[r]-mhat);pA1[r]=__builtin_amdgcn_exp2f(pA1[r]-mhat);} }
;   WAIT_BAR(0);
;   DMA_K(3,0);DMA_V(1,SLOTB);
;   ROT();
;   kload8(kf,kp0+sl_cur);
;   WAIT_BAR(3);
;     ...
;   int t=1;
;     ...
;   for(;t+7<NT;t+=2){
;     STEP(pB0,pB1,pA0,pA1,t,true,true,true);     WAIT_BAR(3); RESC(); ROT();
.LBB0_1275:
	v_max3_f32 v34, v16, v17, v0
	v_max3_f32 v35, v18, v19, v1
	s_and_b32 s18, s87, 0x3fffffc0
	v_max3_f32 v34, v34, v2, v3
	v_max3_f32 v35, v35, v22, v23
	s_lshl_b32 s18, s18, 2
	v_max3_f32 v34, v34, v20, v21
	v_max3_f32 v35, v35, v6, v7
	s_add_i32 s49, s18, 0
	v_max3_f32 v34, v34, v4, v5
	v_max3_f32 v35, v35, v26, v27
	s_add_i32 s49, s49, 0x12000
	v_max3_f32 v34, v34, v24, v25
	v_max3_f32 v35, v35, v10, v11
	s_waitcnt vmcnt(0) lgkmcnt(0)
	s_barrier
	s_cmp_lg_u32 0, -1
	v_max3_f32 v34, v34, v8, v9
	v_max3_f32 v35, v35, v30, v31
	s_mov_b32 s37, 0
	v_max3_f32 v34, v34, v28, v29
	v_max3_f32 v35, v35, v14, v15
	v_lshl_add_u32 v233, v212, 2, s49
	v_max3_f32 v34, v34, v12, v13
	s_nop 0
	v_max_f32_e32 v34, v34, v35
	s_nop 0
	v_mov_b32_e32 v35, v34
	s_nop 1
	v_permlane32_swap_b32_e32 v34, v35
	v_max_f32_e32 v235, v34, v35
	s_nop 0
	v_sub_f32_e32 v0, v0, v235
	v_exp_f32_e32 v64, v0
	v_sub_f32_e32 v0, v17, v235
	v_exp_f32_e32 v81, v0
	v_sub_f32_e32 v0, v1, v235
	v_exp_f32_e32 v65, v0
	v_sub_f32_e32 v0, v18, v235
	v_exp_f32_e32 v82, v0
	v_sub_f32_e32 v0, v2, v235
	v_exp_f32_e32 v66, v0
	v_sub_f32_e32 v0, v19, v235
	v_exp_f32_e32 v83, v0
	v_sub_f32_e32 v0, v3, v235
	v_exp_f32_e32 v67, v0
	v_sub_f32_e32 v0, v20, v235
	v_exp_f32_e32 v84, v0
	v_sub_f32_e32 v0, v4, v235
	v_exp_f32_e32 v68, v0
	v_sub_f32_e32 v0, v21, v235
	v_exp_f32_e32 v85, v0
	v_sub_f32_e32 v0, v5, v235
	v_exp_f32_e32 v69, v0
	v_sub_f32_e32 v0, v22, v235
	v_exp_f32_e32 v86, v0
	v_sub_f32_e32 v0, v6, v235
	v_exp_f32_e32 v70, v0
	v_sub_f32_e32 v0, v23, v235
	v_exp_f32_e32 v87, v0
	v_sub_f32_e32 v0, v7, v235
	v_exp_f32_e32 v71, v0
	v_sub_f32_e32 v0, v24, v235
	v_exp_f32_e32 v88, v0
	v_sub_f32_e32 v0, v8, v235
	v_exp_f32_e32 v72, v0
	v_sub_f32_e32 v0, v25, v235
	v_exp_f32_e32 v89, v0
	v_sub_f32_e32 v0, v9, v235
	v_exp_f32_e32 v73, v0
	v_sub_f32_e32 v0, v26, v235
	v_exp_f32_e32 v90, v0
	v_sub_f32_e32 v0, v10, v235
	v_exp_f32_e32 v74, v0
	v_sub_f32_e32 v0, v27, v235
	v_exp_f32_e32 v91, v0
	v_sub_f32_e32 v0, v11, v235
	v_exp_f32_e32 v75, v0
	v_sub_f32_e32 v0, v28, v235
	v_exp_f32_e32 v92, v0
	v_sub_f32_e32 v0, v12, v235
	v_exp_f32_e32 v76, v0
	v_sub_f32_e32 v0, v29, v235
	v_exp_f32_e32 v93, v0
	v_sub_f32_e32 v0, v13, v235
	v_exp_f32_e32 v77, v0
	v_sub_f32_e32 v0, v30, v235
	v_exp_f32_e32 v94, v0
	v_sub_f32_e32 v0, v14, v235
	v_exp_f32_e32 v78, v0
	v_sub_f32_e32 v0, v31, v235
	v_exp_f32_e32 v95, v0
	v_sub_f32_e32 v0, v15, v235
	v_exp_f32_e32 v79, v0
	v_lshl_add_u64 v[0:1], v[202:203], 0, s[24:25]
	s_mov_b32 s18, m0
	s_mov_b32 m0, s89
	s_nop 0
	global_load_lds_dwordx4 v[0:1], off
	s_mov_b32 m0, s18
	s_cselect_b32 s18, 0, 0
	s_add_i32 s12, s18, s12
	v_lshl_add_u64 v[0:1], v[32:33], 0, s[16:17]
	s_add_i32 s18, s12, 0xa000
	s_mov_b32 s22, m0
	s_mov_b32 m0, s18
	s_nop 0
	global_load_lds_dwordx4 v[0:1], off
	s_mov_b32 m0, s22
	v_lshl_add_u64 v[0:1], v[32:33], 0, s[24:25]
	s_add_i32 s12, s12, 0xc000
	s_mov_b32 s18, m0
	s_mov_b32 m0, s12
	s_nop 0
	global_load_lds_dwordx4 v[0:1], off
	s_mov_b32 m0, s18
	ds_read_b128 v[188:191], v213 offset:8192
	ds_read_b128 v[184:187], v213 offset:8704
	ds_read_b128 v[180:183], v213 offset:10240
	ds_read_b128 v[176:179], v213 offset:10752
	ds_read_b128 v[172:175], v213 offset:12288
	ds_read_b128 v[168:171], v213 offset:12800
	ds_read_b128 v[164:167], v213 offset:14336
	ds_read_b128 v[160:163], v213 offset:14848
	v_sub_f32_e32 v16, v16, v235
	v_exp_f32_e32 v80, v16
	s_waitcnt vmcnt(3) lgkmcnt(0)
	s_barrier
	s_cmp_lt_i32 s91, 9
	s_cbranch_scc1 .LBB0_1291
	s_add_i32 s30, s19, s21
	s_ashr_i32 s31, s30, 31
	s_add_i32 s22, s91, -7
	s_lshl_b64 s[30:31], s[30:31], 14
	s_add_u32 s30, s30, s0
	s_addc_u32 s31, s31, s1
	v_mov_b32_e32 v32, v197
	v_mov_b32_e32 v33, v197
	v_mov_b32_e32 v46, v197
	v_mov_b32_e32 v47, v197
	v_lshl_add_u64 v[204:205], v[198:199], 0, s[30:31]
	s_mov_b64 s[30:31], 0xa000
	v_mov_b32_e32 v34, v197
	v_mov_b32_e32 v35, v197
	v_mov_b32_e32 v36, v197
	v_mov_b32_e32 v37, v197
	v_mov_b32_e32 v38, v197
	v_mov_b32_e32 v39, v197
	v_mov_b32_e32 v40, v197
	v_mov_b32_e32 v41, v197
	v_mov_b32_e32 v42, v197
	v_mov_b32_e32 v43, v197
	v_mov_b32_e32 v44, v197
	v_mov_b32_e32 v45, v197
	v_mov_b64_e32 v[62:63], v[46:47]
	v_mov_b64_e32 v[16:17], v[32:33]
	v_mov_b64_e32 v[0:1], v[32:33]
	s_mov_b32 s12, 1
	v_lshl_add_u64 v[206:207], v[202:203], 0, s[30:31]
	s_mov_b32 s23, 0
	s_movk_i32 s37, 0x4000
	s_movk_i32 s86, 0x2000
	v_mov_b32_e32 v236, 0
	v_mov_b64_e32 v[60:61], v[44:45]
	v_mov_b64_e32 v[58:59], v[42:43]
	v_mov_b64_e32 v[56:57], v[40:41]
	v_mov_b64_e32 v[54:55], v[38:39]
	v_mov_b64_e32 v[52:53], v[36:37]
	v_mov_b64_e32 v[50:51], v[34:35]
	v_mov_b64_e32 v[48:49], v[32:33]
	v_mov_b64_e32 v[18:19], v[34:35]
	v_mov_b64_e32 v[20:21], v[36:37]
	v_mov_b64_e32 v[22:23], v[38:39]
	v_mov_b64_e32 v[24:25], v[40:41]
	v_mov_b64_e32 v[26:27], v[42:43]
	v_mov_b64_e32 v[28:29], v[44:45]
	v_mov_b64_e32 v[30:31], v[46:47]
	v_mov_b64_e32 v[2:3], v[34:35]
	v_mov_b64_e32 v[4:5], v[36:37]
	v_mov_b64_e32 v[6:7], v[38:39]
	v_mov_b64_e32 v[8:9], v[40:41]
	v_mov_b64_e32 v[10:11], v[42:43]
	v_mov_b64_e32 v[12:13], v[44:45]
	v_mov_b64_e32 v[14:15], v[46:47]
	v_xor_b32_e32 v238, 0x80000000, v235
	v_mov_b32_e32 v239, v238
	v_mov_b64_e32 v[240:241], v[238:239]
	v_mov_b64_e32 v[242:243], v[238:239]
	v_mov_b64_e32 v[244:245], v[238:239]
	v_mov_b64_e32 v[246:247], v[238:239]
	v_mov_b64_e32 v[248:249], v[238:239]
	v_mov_b64_e32 v[250:251], v[238:239]
	v_mov_b64_e32 v[252:253], v[238:239]
	v_readfirstlane_b32 s98, v206
	v_readfirstlane_b32 s99, v207
	v_readfirstlane_b32 s100, v204
	v_readfirstlane_b32 s101, v205
.LBB0_1277:
	s_lshl_b32 s18, s23, 1
	v_add_u32_e32 v237, s18, v214
	ds_read_b64_tr_b16 v[192:193], v237 offset:24576
	v_add_f32_e32 v112, v80, v81
	v_add_f32_e32 v112, v82, v112
	v_add_f32_e32 v112, v83, v112
	v_add_f32_e32 v112, v84, v112
	v_add_f32_e32 v128, v85, v112
	s_waitcnt lgkmcnt(8)
	v_mfma_f32_32x32x16_bf16 v[112:127], v[188:191], v[156:159], v[238:253]
	v_cvt_pk_bf16_f32 v148, v80, v81
	v_cvt_pk_bf16_f32 v149, v82, v83
	ds_read_b64_tr_b16 v[194:195], v237 offset:25088
	s_waitcnt lgkmcnt(8)
	v_mfma_f32_32x32x16_bf16 v[96:111], v[184:187], v[156:159], v[238:253]
	v_add_f32_e32 v80, v86, v128
	v_add_f32_e32 v80, v87, v80
	v_add_f32_e32 v80, v88, v80
	v_add_f32_e32 v82, v89, v80
	v_cvt_pk_bf16_f32 v150, v84, v85
	v_cvt_pk_bf16_f32 v151, v86, v87
	ds_read_b64_tr_b16 v[80:81], v237 offset:28672
	s_waitcnt lgkmcnt(8)
	v_mfma_f32_32x32x16_bf16 v[112:127], v[180:183], v[152:155], v[112:127]
	v_add_f32_e32 v82, v90, v82
	v_add_f32_e32 v82, v91, v82
	v_add_f32_e32 v82, v92, v82
	v_add_f32_e32 v84, v93, v82
	v_cvt_pk_bf16_f32 v140, v88, v89
	v_cvt_pk_bf16_f32 v141, v90, v91
	ds_read_b64_tr_b16 v[82:83], v237 offset:29184
	s_waitcnt lgkmcnt(8)
	v_mfma_f32_32x32x16_bf16 v[96:111], v[176:179], v[152:155], v[96:111]
	v_add_f32_e32 v84, v94, v84
	v_add_f32_e32 v84, v95, v84
	v_add_f32_e32 v84, v64, v84
	v_add_f32_e32 v86, v65, v84
	v_cvt_pk_bf16_f32 v142, v92, v93
	v_cvt_pk_bf16_f32 v143, v94, v95
	ds_read_b64_tr_b16 v[84:85], v237 offset:32768
	s_waitcnt lgkmcnt(8)
	v_mfma_f32_32x32x16_bf16 v[112:127], v[172:175], v[144:147], v[112:127]
	v_add_f32_e32 v86, v66, v86
	v_add_f32_e32 v86, v67, v86
	v_add_f32_e32 v86, v68, v86
	v_add_f32_e32 v88, v69, v86
	v_cvt_pk_bf16_f32 v132, v64, v65
	v_cvt_pk_bf16_f32 v133, v66, v67
	ds_read_b64_tr_b16 v[86:87], v237 offset:33280
	s_waitcnt lgkmcnt(8)
	v_mfma_f32_32x32x16_bf16 v[96:111], v[168:171], v[144:147], v[96:111]
	v_add_f32_e32 v64, v70, v88
	v_add_f32_e32 v64, v71, v64
	v_add_f32_e32 v64, v72, v64
	v_add_f32_e32 v66, v73, v64
	v_cvt_pk_bf16_f32 v134, v68, v69
	v_cvt_pk_bf16_f32 v135, v70, v71
	ds_read_b64_tr_b16 v[64:65], v237 offset:36864
	s_waitcnt lgkmcnt(8)
	v_mfma_f32_32x32x16_bf16 v[112:127], v[164:167], v[136:139], v[112:127]
	v_add_f32_e32 v66, v74, v66
	v_add_f32_e32 v66, v75, v66
	v_add_f32_e32 v66, v76, v66
	v_add_f32_e32 v68, v77, v66
	v_cvt_pk_bf16_f32 v128, v72, v73
	v_cvt_pk_bf16_f32 v129, v74, v75
	ds_read_b64_tr_b16 v[66:67], v237 offset:37376
	s_waitcnt lgkmcnt(8)
	v_mfma_f32_32x32x16_bf16 v[96:111], v[160:163], v[136:139], v[96:111]
	v_add_f32_e32 v68, v78, v68
	v_add_f32_e32 v68, v79, v68
	v_add_f32_e32 v236, v236, v68
	v_cvt_pk_bf16_f32 v130, v76, v77
	v_cvt_pk_bf16_f32 v131, v78, v79
	s_add_u32 s30, s98, 0xffffe000
	s_addc_u32 s31, s99, -1
	s_add_i32 s18, s86, s89
	s_nop 0
	s_mov_b32 s23, m0
	s_mov_b32 m0, s18
	s_nop 0
	global_load_lds_dwordx4 v196, s[30:31]
	s_mov_b32 m0, s23
	s_add_u32 s30, s100, 0xffffc000
	s_addc_u32 s31, s101, -1
	s_lshl_b32 s18, s37, 1
	s_add_i32 s18, s18, s90
	s_mov_b32 s23, m0
	s_mov_b32 m0, s18
	s_nop 0
	global_load_lds_dwordx4 v196, s[30:31]
	s_mov_b32 m0, s23
	s_add_u32 s30, s100, 0xffffe000
	s_addc_u32 s31, s101, -1
	s_addk_i32 s18, 0x2000
	s_mov_b32 s23, m0
	s_mov_b32 m0, s18
	s_nop 0
	global_load_lds_dwordx4 v196, s[30:31]
	s_mov_b32 m0, s23
	v_max_f32_e32 v68, v113, v112
	v_max3_f32 v69, v114, v115, v97
	v_max3_f32 v68, v68, v96, v98
	v_max3_f32 v68, v68, v99, v116
	v_max3_f32 v69, v69, v118, v119
	v_max3_f32 v68, v68, v117, v100
	v_max3_f32 v69, v69, v102, v103
	v_max3_f32 v68, v68, v101, v120
	v_max3_f32 v69, v69, v122, v123
	v_max3_f32 v68, v68, v121, v104
	v_max3_f32 v69, v69, v106, v107
	v_max3_f32 v68, v68, v105, v124
	v_max3_f32 v69, v69, v126, v127
	v_max3_f32 v68, v68, v125, v108
	v_max3_f32 v69, v69, v110, v111
	v_max3_f32 v68, v68, v109, v69
	v_cmp_lt_f32_e32 vcc, s71, v68
	s_cmp_lg_u64 vcc, 0
	s_cselect_b64 s[50:51], -1, 0
	s_cbranch_vccnz .LBB0_1285

.LBB0_1280:
	s_add_i32 s18, s37, 0x2000
	s_lshl_b32 s23, s86, 1
	v_add_u32_e32 v237, s23, v214
	ds_read_b64_tr_b16 v[180:181], v237 offset:24576
	s_cmpk_lg_i32 s37, 0x4000
	s_cselect_b32 s86, s18, 0
	v_add_f32_e32 v80, v112, v113
	v_add_f32_e32 v80, v114, v80
	v_add_f32_e32 v80, v115, v80
	v_add_f32_e32 v80, v116, v80
	v_add_f32_e32 v128, v117, v80
	s_waitcnt lgkmcnt(8)
	v_mfma_f32_32x32x16_bf16 v[80:95], v[192:195], v[156:159], v[238:253]
	v_cvt_pk_bf16_f32 v148, v112, v113
	v_cvt_pk_bf16_f32 v149, v114, v115
	ds_read_b64_tr_b16 v[182:183], v237 offset:25088
	s_waitcnt lgkmcnt(8)
	v_mfma_f32_32x32x16_bf16 v[64:79], v[188:191], v[156:159], v[238:253]
	v_add_f32_e32 v112, v118, v128
	v_add_f32_e32 v112, v119, v112
	v_add_f32_e32 v112, v120, v112
	v_add_f32_e32 v114, v121, v112
	v_cvt_pk_bf16_f32 v150, v116, v117
	v_cvt_pk_bf16_f32 v151, v118, v119
	ds_read_b64_tr_b16 v[112:113], v237 offset:28672
	s_waitcnt lgkmcnt(8)
	v_mfma_f32_32x32x16_bf16 v[80:95], v[184:187], v[152:155], v[80:95]
	v_add_f32_e32 v114, v122, v114
	v_add_f32_e32 v114, v123, v114
	v_add_f32_e32 v114, v124, v114
	v_add_f32_e32 v116, v125, v114
	v_cvt_pk_bf16_f32 v140, v120, v121
	v_cvt_pk_bf16_f32 v141, v122, v123
	ds_read_b64_tr_b16 v[114:115], v237 offset:29184
	s_waitcnt lgkmcnt(8)
	v_mfma_f32_32x32x16_bf16 v[64:79], v[176:179], v[152:155], v[64:79]
	v_add_f32_e32 v116, v126, v116
	v_add_f32_e32 v116, v127, v116
	v_add_f32_e32 v116, v96, v116
	v_add_f32_e32 v118, v97, v116
	v_cvt_pk_bf16_f32 v142, v124, v125
	v_cvt_pk_bf16_f32 v143, v126, v127
	ds_read_b64_tr_b16 v[116:117], v237 offset:32768
	s_waitcnt lgkmcnt(8)
	v_mfma_f32_32x32x16_bf16 v[80:95], v[172:175], v[144:147], v[80:95]
	v_add_f32_e32 v118, v98, v118
	v_add_f32_e32 v118, v99, v118
	v_add_f32_e32 v118, v100, v118
	v_add_f32_e32 v120, v101, v118
	v_cvt_pk_bf16_f32 v132, v96, v97
	v_cvt_pk_bf16_f32 v133, v98, v99
	ds_read_b64_tr_b16 v[118:119], v237 offset:33280
	s_waitcnt lgkmcnt(8)
	v_mfma_f32_32x32x16_bf16 v[64:79], v[168:171], v[144:147], v[64:79]
	v_add_f32_e32 v96, v102, v120
	v_add_f32_e32 v96, v103, v96
	v_add_f32_e32 v96, v104, v96
	v_add_f32_e32 v98, v105, v96
	v_cvt_pk_bf16_f32 v134, v100, v101
	v_cvt_pk_bf16_f32 v135, v102, v103
	ds_read_b64_tr_b16 v[96:97], v237 offset:36864
	s_waitcnt lgkmcnt(8)
	v_mfma_f32_32x32x16_bf16 v[80:95], v[164:167], v[136:139], v[80:95]
	v_add_f32_e32 v98, v106, v98
	v_add_f32_e32 v98, v107, v98
	v_add_f32_e32 v98, v108, v98
	v_add_f32_e32 v100, v109, v98
	v_cvt_pk_bf16_f32 v128, v104, v105
	v_cvt_pk_bf16_f32 v129, v106, v107
	ds_read_b64_tr_b16 v[98:99], v237 offset:37376
	s_waitcnt lgkmcnt(8)
	v_mfma_f32_32x32x16_bf16 v[64:79], v[160:163], v[136:139], v[64:79]
	v_add_f32_e32 v100, v110, v100
	v_add_f32_e32 v100, v111, v100
	v_add_f32_e32 v236, v236, v100
	v_cvt_pk_bf16_f32 v130, v108, v109
	v_cvt_pk_bf16_f32 v131, v110, v111
	s_add_i32 s18, s37, s89
	s_mov_b32 s23, m0
	s_mov_b32 m0, s18
	s_nop 0
	global_load_lds_dwordx4 v196, s[98:99]
	s_mov_b32 m0, s23
	s_lshl_b32 s18, s86, 1
	s_add_i32 s18, s18, s90
	s_mov_b32 s23, m0
	s_mov_b32 m0, s18
	s_nop 0
	global_load_lds_dwordx4 v196, s[100:101]
	s_mov_b32 m0, s23
	s_add_u32 s30, s100, 0x2000
	s_addc_u32 s31, s101, 0
	s_addk_i32 s18, 0x2000
	s_mov_b32 s23, m0
	s_mov_b32 m0, s18
	s_nop 0
	global_load_lds_dwordx4 v196, s[30:31]
	s_mov_b32 m0, s23
	v_max_f32_e32 v100, v81, v80
	v_max3_f32 v101, v82, v83, v65
	v_max3_f32 v100, v100, v64, v66
	v_max3_f32 v100, v100, v67, v84
	v_max3_f32 v101, v101, v86, v87
	v_max3_f32 v100, v100, v85, v68
	v_max3_f32 v101, v101, v70, v71
	v_max3_f32 v100, v100, v69, v88
	v_max3_f32 v101, v101, v90, v91
	v_max3_f32 v100, v100, v89, v72
	v_max3_f32 v101, v101, v74, v75
	v_max3_f32 v100, v100, v73, v92
	v_max3_f32 v101, v101, v94, v95
	v_max3_f32 v100, v100, v93, v76
	v_max3_f32 v101, v101, v78, v79
	v_max3_f32 v100, v100, v77, v101
	v_cmp_lt_f32_e32 vcc, s71, v100
	s_cmp_lg_u64 vcc, 0
	s_cselect_b64 s[50:51], -1, 0
	s_cbranch_vccnz .LBB0_1288

; #define WAIT_BAR(N) asm volatile("s_waitcnt vmcnt(" #N ") lgkmcnt(0)\n\ts_barrier":::"memory")
;   #define RESC() do{ if(resc){ asm volatile("s_waitcnt lgkmcnt(0)":::"memory"); \
;       _Pragma("unroll") for(int d_=0;d_<4;++d_) _Pragma("unroll") for(int r=0;r<16;++r)o[d_][r]*=wsf[crow(r,hi)]; } }while(0)
;   #define ROT() do{sl_prev=sl_cur;sl_cur=sl_next;sl_next=(sl_next==(NSLOT-1)*SLOTB)?0:sl_next+SLOTB;}while(0)
; template<int THRL> __device__ __forceinline__ void attn_unit(int b,int hc,int qb,const bf16*Q,const bf16*__restrict__ K,const bf16*__restrict__ V,bf16*O,char*shm){
;     ...
;   for(;t+7<NT;t+=2){
;     STEP(pB0,pB1,pA0,pA1,t,true,true,true);     WAIT_BAR(3); RESC(); ROT();
;     STEP(pA0,pA1,pB0,pB1,t+1,true,true,true);   WAIT_BAR(3); RESC(); ROT();
;   }
.LBB0_1283:
	s_add_u32 s100, s100, 0x8000
	s_addc_u32 s101, s101, 0
	s_add_u32 s98, s98, 0x4000
	s_addc_u32 s99, s99, 0
	s_add_i32 s12, s12, 2
	s_add_i32 s18, s86, 0x2000
	s_cmpk_lg_i32 s86, 0x4000
	s_cselect_b32 s18, s18, 0
	s_cmp_ge_i32 s12, s22
	s_cbranch_scc1 .Lattn_exit_fix
	s_mov_b32 s23, s37
	s_mov_b32 s37, s18
	s_branch .LBB0_1277
.Lattn_exit_fix:
	v_lshl_add_u64 v[204:205], s[100:101], 0, v[196:197]
	v_lshl_add_u64 v[206:207], s[98:99], 0, v[196:197]
	s_branch .LBB0_1292
.LBB0_1285:
	v_mov_b32_e32 v69, v68
	s_nop 1
	v_permlane32_swap_b32_e32 v68, v69
	v_max_f32_e32 v68, v69, v68
	v_max_f32_e32 v68, v68, v68
	v_max_f32_e32 v69, 0, v68
	v_exp_f32_e64 v68, -v69
	s_and_saveexec_b64 s[52:53], s[2:3]
	ds_write_b32 v233, v68
	s_or_b64 exec, exec, s[52:53]
	v_sub_f32_e32 v127, v127, v69
	v_sub_f32_e32 v126, v126, v69
	v_sub_f32_e32 v125, v125, v69
	v_sub_f32_e32 v124, v124, v69
	v_sub_f32_e32 v123, v123, v69
	v_sub_f32_e32 v122, v122, v69
	v_sub_f32_e32 v121, v121, v69
	v_sub_f32_e32 v120, v120, v69
	v_sub_f32_e32 v119, v119, v69
	v_sub_f32_e32 v118, v118, v69
	v_sub_f32_e32 v117, v117, v69
	v_sub_f32_e32 v116, v116, v69
	v_sub_f32_e32 v115, v115, v69
	v_sub_f32_e32 v114, v114, v69
	v_sub_f32_e32 v113, v113, v69
	v_sub_f32_e32 v112, v112, v69
	v_sub_f32_e32 v111, v111, v69
	v_sub_f32_e32 v110, v110, v69
	v_sub_f32_e32 v109, v109, v69
	v_sub_f32_e32 v108, v108, v69
	v_sub_f32_e32 v107, v107, v69
	v_sub_f32_e32 v106, v106, v69
	v_sub_f32_e32 v105, v105, v69
	v_sub_f32_e32 v104, v104, v69
	v_sub_f32_e32 v103, v103, v69
	v_sub_f32_e32 v102, v102, v69
	v_sub_f32_e32 v101, v101, v69
	v_sub_f32_e32 v100, v100, v69
	v_sub_f32_e32 v99, v99, v69
	v_sub_f32_e32 v98, v98, v69
	v_sub_f32_e32 v97, v97, v69
	v_sub_f32_e32 v96, v96, v69
	v_add_f32_e32 v235, v235, v69
	v_xor_b32_e32 v238, 0x80000000, v235
	v_mov_b32_e32 v239, v238
	v_mov_b64_e32 v[240:241], v[238:239]
	v_mov_b64_e32 v[242:243], v[238:239]
	v_mov_b64_e32 v[244:245], v[238:239]
	v_mov_b64_e32 v[246:247], v[238:239]
	v_mov_b64_e32 v[248:249], v[238:239]
	v_mov_b64_e32 v[250:251], v[238:239]
	v_mov_b64_e32 v[252:253], v[238:239]
	v_mul_f32_e32 v236, v236, v68
	s_branch .LBB0_1278
.LBB0_1288:
	v_mov_b32_e32 v101, v100
	s_nop 1
	v_permlane32_swap_b32_e32 v100, v101
	v_max_f32_e32 v100, v101, v100
	v_max_f32_e32 v100, v100, v100
	v_max_f32_e32 v101, 0, v100
	v_exp_f32_e64 v100, -v101
	s_and_saveexec_b64 s[52:53], s[2:3]
	ds_write_b32 v233, v100
	s_or_b64 exec, exec, s[52:53]
	v_sub_f32_e32 v95, v95, v101
	v_sub_f32_e32 v94, v94, v101
	v_sub_f32_e32 v93, v93, v101
	v_sub_f32_e32 v92, v92, v101
	v_sub_f32_e32 v91, v91, v101
	v_sub_f32_e32 v90, v90, v101
	v_sub_f32_e32 v89, v89, v101
	v_sub_f32_e32 v88, v88, v101
	v_sub_f32_e32 v87, v87, v101
	v_sub_f32_e32 v86, v86, v101
	v_sub_f32_e32 v85, v85, v101
	v_sub_f32_e32 v84, v84, v101
	v_sub_f32_e32 v83, v83, v101
	v_sub_f32_e32 v82, v82, v101
	v_sub_f32_e32 v81, v81, v101
	v_sub_f32_e32 v80, v80, v101
	v_sub_f32_e32 v79, v79, v101
	v_sub_f32_e32 v78, v78, v101
	v_sub_f32_e32 v77, v77, v101
	v_sub_f32_e32 v76, v76, v101
	v_sub_f32_e32 v75, v75, v101
	v_sub_f32_e32 v74, v74, v101
	v_sub_f32_e32 v73, v73, v101
	v_sub_f32_e32 v72, v72, v101
	v_sub_f32_e32 v71, v71, v101
	v_sub_f32_e32 v70, v70, v101
	v_sub_f32_e32 v69, v69, v101
	v_sub_f32_e32 v68, v68, v101
	v_sub_f32_e32 v67, v67, v101
	v_sub_f32_e32 v66, v66, v101
	v_sub_f32_e32 v65, v65, v101
	v_sub_f32_e32 v64, v64, v101
	v_add_f32_e32 v235, v235, v101
	v_xor_b32_e32 v238, 0x80000000, v235
	v_mov_b32_e32 v239, v238
	v_mov_b64_e32 v[240:241], v[238:239]
	v_mov_b64_e32 v[242:243], v[238:239]
	v_mov_b64_e32 v[244:245], v[238:239]
	v_mov_b64_e32 v[246:247], v[238:239]
	v_mov_b64_e32 v[248:249], v[238:239]
	v_mov_b64_e32 v[250:251], v[238:239]
	v_mov_b64_e32 v[252:253], v[238:239]
	v_mul_f32_e32 v236, v236, v100
	s_branch .LBB0_1281

; __global__ void __launch_bounds__(NWAVES * 64, 2) mega_fwd(Args args) {
	.amdhsa_kernel _Z8mega_fwd4Args
		.amdhsa_group_segment_fixed_size 0
		.amdhsa_private_segment_fixed_size 0
		.amdhsa_kernarg_size 512
		.amdhsa_user_sgpr_count 2
		.amdhsa_user_sgpr_dispatch_ptr 0
		.amdhsa_user_sgpr_queue_ptr 0
		.amdhsa_user_sgpr_kernarg_segment_ptr 1
		.amdhsa_user_sgpr_dispatch_id 0
		.amdhsa_user_sgpr_kernarg_preload_length 0
		.amdhsa_user_sgpr_kernarg_preload_offset 0
		.amdhsa_user_sgpr_private_segment_size 0
		.amdhsa_uses_dynamic_stack 0
		.amdhsa_enable_private_segment 0
		.amdhsa_system_sgpr_workgroup_id_x 1
		.amdhsa_system_sgpr_workgroup_id_y 0
		.amdhsa_system_sgpr_workgroup_id_z 0
		.amdhsa_system_sgpr_workgroup_info 0
		.amdhsa_system_vgpr_workitem_id 2
		.amdhsa_next_free_vgpr 256
		.amdhsa_next_free_sgpr 102
		.amdhsa_accum_offset 256
		.amdhsa_reserve_vcc 1
		.amdhsa_float_round_mode_32 0
		.amdhsa_float_round_mode_16_64 0
		.amdhsa_float_denorm_mode_32 3
		.amdhsa_float_denorm_mode_16_64 3
		.amdhsa_dx10_clamp 1
		.amdhsa_ieee_mode 1
		.amdhsa_fp16_overflow 0
		.amdhsa_tg_split 0
		.amdhsa_exception_fp_ieee_invalid_op 0
		.amdhsa_exception_fp_denorm_src 0
		.amdhsa_exception_fp_ieee_div_zero 0
		.amdhsa_exception_fp_ieee_overflow 0
		.amdhsa_exception_fp_ieee_underflow 0
		.amdhsa_exception_fp_ieee_inexact 0
		.amdhsa_exception_int_div_zero 0
	.end_amdhsa_kernel

; __global__ void __launch_bounds__(NWAVES * 64, 2) mega_fwd(Args args) {
amdhsa.kernels:
  - .agpr_count:     0
    .args:
      - .offset:         0
        .size:           256
        .value_kind:     by_value
      - .offset:         256
        .size:           4
        .value_kind:     hidden_block_count_x
      - .offset:         260
        .size:           4
        .value_kind:     hidden_block_count_y
      - .offset:         264
        .size:           4
        .value_kind:     hidden_block_count_z
      - .offset:         268
        .size:           2
        .value_kind:     hidden_group_size_x
      - .offset:         270
        .size:           2
        .value_kind:     hidden_group_size_y
      - .offset:         272
        .size:           2
        .value_kind:     hidden_group_size_z
      - .offset:         274
        .size:           2
        .value_kind:     hidden_remainder_x
      - .offset:         276
        .size:           2
        .value_kind:     hidden_remainder_y
      - .offset:         278
        .size:           2
        .value_kind:     hidden_remainder_z
      - .offset:         296
        .size:           8
        .value_kind:     hidden_global_offset_x
      - .offset:         304
        .size:           8
        .value_kind:     hidden_global_offset_y
      - .offset:         312
        .size:           8
        .value_kind:     hidden_global_offset_z
      - .offset:         320
        .size:           2
        .value_kind:     hidden_grid_dims
      - .offset:         344
        .size:           8
        .value_kind:     hidden_multigrid_sync_arg
      - .offset:         376
        .size:           4
        .value_kind:     hidden_dynamic_lds_size
    .group_segment_fixed_size: 0
    .kernarg_segment_align: 8
    .kernarg_segment_size: 512
    .language:       OpenCL C
    .language_version:
      - 2
      - 0
    .max_flat_workgroup_size: 512
    .name:           _Z8mega_fwd4Args
    .private_segment_fixed_size: 0
    .sgpr_count:     108
    .sgpr_spill_count: 76
    .symbol:         _Z8mega_fwd4Args.kd
    .uniform_work_group_size: 1
    .uses_dynamic_stack: false
    .vgpr_count:     256
    .vgpr_spill_count: 0
    .wavefront_size: 64
